# per-XCD attention queues: the short context-query units of queues 0 and 1 handed out in a second pass after queue 2 (longest units first, shortest last)
# baseline (speedup 1.0000x reference)
; template <int Q>
; DI void attn_queue(const Params& p, int l, char* smem, int* s_unit, int cb) {
;     const bool ctxu = l < DEPTH - 1;
;     const int total = (Q == 0) ? (ctxu ? 576 : 512) : (Q == 1) ? (ctxu ? 960 : 768) : 768;
; DI void attn_phase(const Params& p, int l, char* smem, int cb) {
;     __shared__ int s_unit;
;     attn_queue<0>(p, l, smem, &s_unit, cb);
;     attn_queue<1>(p, l, smem, &s_unit, cb);
;     attn_queue<2>(p, l, smem, &s_unit, cb);
; }
.LBB0_69:
	s_andn2_b64 vcc, exec, s[4:5]
	s_cbranch_vccnz .LBB0_136
	v_writelane_b32 v255, 0, 41
.Lattn_pass:
	s_cmp_lt_i32 s60, 3
	s_cselect_b64 s[44:45], -1, 0
	s_and_b64 s[4:5], s[44:45], exec
	s_movk_i32 s4, 0x240
	s_cselect_b32 s28, s4, 0x200
	s_lshl_b32 s4, s60, 6
	s_lshl_b32 s48, s60, 2
	s_ashr_i32 s5, s4, 31
	s_ashr_i32 s49, s48, 31
	s_ashr_i32 s61, s60, 31
	s_lshl_b64 s[46:47], s[4:5], 2
	s_branch .LBB0_72

; template <int Q>
; DI void attn_queue(const Params& p, int l, char* smem, int* s_unit, int cb) {
;     ...
;         if (Q == 0) {
;             int b, head, qt, t1 = 0, n1 = 36;
;             if (u < 512) { b = u >> 6; head = (u >> 4) & 3; qt = u & 15; }
;             else { const int v = u - 512; b = v >> 3; head = (v >> 1) & 3; qt = 16 + (v & 1); t1 = 32; n1 = 4; }
;             attn_unit<0>(p, l, b, head, qt, head * 64, 256 + head * 64, head * 64, 768 + head * 64, head * 64, t1, n1, 0, 0, smem);
.LBB0_72:
	s_and_saveexec_b64 s[4:5], s[54:55]
	s_cbranch_execz .LBB0_76
	s_mov_b64 s[8:9], exec
	v_mbcnt_lo_u32_b32 v0, s8, 0
	v_mbcnt_hi_u32_b32 v0, s9, v0
	v_cmp_eq_u32_e32 vcc, 0, v0
	s_and_saveexec_b64 s[6:7], vcc
	s_cbranch_execz .LBB0_75
	ds_read_b32 v2, v193 offset:8
	s_load_dwordx2 s[34:35], s[0:1], 0x100
	s_lshl_b64 s[40:41], s[48:49], 2
	s_waitcnt lgkmcnt(0)
	s_add_u32 s34, s34, s40
	s_addc_u32 s35, s35, s41
	v_readfirstlane_b32 s40, v2
	s_nop 0
	s_cmp_eq_u32 s40, 0
	s_cbranch_scc1 .Lq0_glob
	v_readlane_b32 s8, v254, 0
	s_nop 0
	s_and_b32 s8, s8, 7
	v_readlane_b32 s41, v255, 41
	s_nop 0
	s_lshl_b32 s9, s8, 8
	s_lshl_b32 s40, s60, 4
	s_add_i32 s9, s9, s40
	s_addk_i32 s9, 0x2420
	s_lshl_b32 s40, s41, 6
	s_add_i32 s9, s9, s40
	s_add_u32 s34, s68, s9
	s_addc_u32 s35, s69, 0
	v_mov_b32_e32 v1, 1
	global_atomic_add v1, v193, v1, s[34:35] sc0
	s_waitcnt vmcnt(0)
	v_readfirstlane_b32 s9, v1
	s_nop 0
	s_lshr_b32 s40, s28, 3
	s_cmp_lg_u32 s41, 0
	s_cselect_b32 s40, s40, 64
	s_cselect_b32 s41, 64, 0
	s_add_i32 s9, s9, s41
	s_lshl_b32 s34, s8, 6
	s_add_i32 s34, s34, s9
	s_lshl_b32 s35, s8, 3
	s_add_i32 s35, s35, s9
	s_addk_i32 s35, 0x1c0
	s_cmp_lt_u32 s9, 64
	s_cselect_b32 s34, s34, s35
	s_cmp_lt_u32 s9, s40
	s_cselect_b32 s34, s34, s28
	v_mov_b32_e32 v1, s34
	s_branch .LBB0_75

; template <int Q>
; DI void attn_queue(const Params& p, int l, char* smem, int* s_unit, int cb) {
;     ...
;         } else if (Q == 1) {
;             int b, head, qt, t1 = 0, n1 = 36; bool cgrp = false;
;             if (u < 768) { b = u / 96; head = (u >> 4) % 6; qt = u & 15; }
;             else if (u < 864) { const int v = u - 768; b = v / 12; head = (v >> 1) % 6; qt = 16 + (v & 1); t1 = 32; n1 = 4; }
;             else { const int v = u - 864; b = v / 12; head = (v >> 1) % 6; qt = 16 + (v & 1); t1 = 32; n1 = 4; cgrp = true; }
;             int qcol, kcol, vfeat, gcol, mixcol;
;             if (!cgrp) { const int kv = head / 3; qcol = 1024 + head * 64; kcol = 1408 + kv * 64; vfeat = 256 + kv * 64; gcol = 1664 + head * 64; mixcol = 256 + head * 64; }
;             else { qcol = 2048 + head * 64; kcol = 2432 + head * 64; vfeat = 384 + head * 64; gcol = 3200 + head * 64; mixcol = 640 + head * 64; }
;             attn_unit<1>(p, l, b, head, qt, qcol, kcol, vfeat, gcol, mixcol, t1, n1, 0, 0, smem);
.LBB0_86:
	s_and_saveexec_b64 s[4:5], s[54:55]
	s_cbranch_execz .LBB0_90
	s_mov_b64 s[8:9], exec
	v_mbcnt_lo_u32_b32 v0, s8, 0
	v_mbcnt_hi_u32_b32 v0, s9, v0
	v_cmp_eq_u32_e32 vcc, 0, v0
	s_and_saveexec_b64 s[6:7], vcc
	s_cbranch_execz .LBB0_89
	ds_read_b32 v2, v193 offset:8
	s_load_dwordx2 s[34:35], s[0:1], 0x100
	s_lshl_b64 s[40:41], s[48:49], 2
	s_waitcnt lgkmcnt(0)
	s_add_u32 s34, s34, s40
	s_addc_u32 s35, s35, s41
	v_readfirstlane_b32 s40, v2
	s_nop 0
	s_cmp_eq_u32 s40, 0
	s_cbranch_scc1 .Lq1_glob
	v_readlane_b32 s8, v254, 0
	s_nop 0
	s_and_b32 s8, s8, 7
	v_readlane_b32 s41, v255, 41
	s_nop 0
	s_lshl_b32 s9, s8, 8
	s_lshl_b32 s40, s60, 4
	s_add_i32 s9, s9, s40
	s_addk_i32 s9, 0x2424
	s_lshl_b32 s40, s41, 6
	s_add_i32 s9, s9, s40
	s_add_u32 s34, s68, s9
	s_addc_u32 s35, s69, 0
	v_mov_b32_e32 v1, 1
	global_atomic_add v1, v193, v1, s[34:35] sc0
	s_waitcnt vmcnt(0)
	v_readfirstlane_b32 s9, v1
	s_nop 0
	s_lshr_b32 s40, s28, 3
	s_cmp_lg_u32 s41, 0
	s_cselect_b32 s40, s40, 0x60
	s_cselect_b32 s41, 0x60, 0
	s_add_i32 s9, s9, s41
	s_mul_i32 s35, s8, 12
	s_add_i32 s35, s35, s9
	s_mul_i32 s34, s8, 0x60
	s_add_i32 s34, s34, s9
	s_add_i32 s8, s35, 0x2a0
	s_cmp_lt_u32 s9, 0x60
	s_cselect_b32 s34, s34, s8
	s_add_i32 s8, s35, 0x2f4
	s_cmp_lt_u32 s9, 0x6c
	s_cselect_b32 s34, s34, s8
	s_cmp_lt_u32 s9, s40
	s_cselect_b32 s34, s34, s28
	v_mov_b32_e32 v1, s34
	s_branch .LBB0_89

; template <int Q>
; DI void attn_queue(const Params& p, int l, char* smem, int* s_unit, int cb) {
;     ...
;         } else {
;             const int b = u / 96, head = (u >> 4) % 6, qt = u & 15;
;             const int t1 = min(max(2 * qt - 4, 0), 24), n1 = min(max(2 * qt + 1 - 4, 0), 24) + 8 - t1;
;             attn_unit<2>(p, l, b, head, qt, 2048 + head * 64, 2432 + head * 64, 384 + head * 64, 3200 + head * 64, 640 + head * 64, t1, n1, 32, 4, smem);
;         }
.LBB0_109:
	s_and_saveexec_b64 s[4:5], s[54:55]
	s_cbranch_execz .LBB0_113
	s_mov_b64 s[8:9], exec
	v_mbcnt_lo_u32_b32 v0, s8, 0
	v_mbcnt_hi_u32_b32 v0, s9, v0
	v_cmp_eq_u32_e32 vcc, 0, v0
	s_and_saveexec_b64 s[6:7], vcc
	s_cbranch_execz .LBB0_112
	ds_read_b32 v2, v193 offset:8
	s_load_dwordx2 s[28:29], s[0:1], 0x100
	s_lshl_b64 s[34:35], s[48:49], 2
	s_waitcnt lgkmcnt(0)
	s_add_u32 s28, s28, s34
	s_addc_u32 s29, s29, s35
	v_readfirstlane_b32 s34, v2
	s_nop 0
	s_cmp_eq_u32 s34, 0
	s_cbranch_scc1 .Lq2_glob
	v_readlane_b32 s8, v254, 0
	s_nop 0
	s_and_b32 s8, s8, 7
	v_readlane_b32 s35, v255, 41
	s_nop 0
	s_lshl_b32 s9, s8, 8
	s_lshl_b32 s34, s60, 4
	s_add_i32 s9, s9, s34
	s_addk_i32 s9, 0x2428
	s_lshl_b32 s34, s35, 6
	s_add_i32 s9, s9, s34
	s_add_u32 s28, s68, s9
	s_addc_u32 s29, s69, 0
	v_mov_b32_e32 v1, 1
	global_atomic_add v1, v193, v1, s[28:29] sc0
	s_waitcnt vmcnt(0)
	v_readfirstlane_b32 s9, v1
	s_nop 0
	s_cmp_lg_u32 s35, 0
	s_cselect_b32 s34, 0, 0x60
	s_mul_i32 s28, s8, 0x60
	s_add_i32 s28, s28, s9
	s_cmp_lt_u32 s9, s34
	s_cselect_b32 s28, s28, 0x300
	v_mov_b32_e32 v1, s28
	s_branch .LBB0_112

; DI void attn_phase(const Params& p, int l, char* smem, int cb) {
;     __shared__ int s_unit;
;     attn_queue<0>(p, l, smem, &s_unit, cb);
;     attn_queue<1>(p, l, smem, &s_unit, cb);
;     attn_queue<2>(p, l, smem, &s_unit, cb);
; }
.Lattn_pass_end:
	v_readlane_b32 s4, v255, 41
	s_nop 0
	s_cmp_lg_u32 s4, 0
	s_cbranch_scc1 .LBB0_136
	ds_read_b32 v0, v193 offset:8
	s_waitcnt lgkmcnt(0)
	v_readfirstlane_b32 s4, v0
	s_nop 0
	s_cmp_eq_u32 s4, 0
	s_cbranch_scc1 .LBB0_136
	v_writelane_b32 v255, 1, 41
	s_branch .Lattn_pass
